# phase-1 tail weight conversions (ffn1 down, w_in) rewritten by hand: 8 loads in flight per item, 2-item software pipeline, v_cvt_pk_bf16_f32
# speedup vs baseline: 1.0033x; 1.0033x over previous
.LBB0_87:
	s_abs_i32 s0, s30
	v_cvt_f32_u32_e32 v0, s0
	s_sub_i32 s1, 0, s0
	v_rcp_iflag_f32_e32 v0, v0
	s_nop 0
	v_mul_f32_e32 v0, 0x4f7ffffe, v0
	v_cvt_u32_f32_e32 v0, v0
	s_nop 0
	v_readfirstlane_b32 s3, v0
	s_mul_i32 s1, s1, s3
	s_mul_hi_u32 s1, s3, s1
	s_add_i32 s3, s3, s1
	s_mul_hi_u32 s1, s3, 0x580
	s_mul_i32 s1, s1, s0
	s_sub_i32 s1, 0x580, s1
	s_sub_i32 s3, s1, s0
	s_cmp_ge_u32 s1, s0
	s_cselect_b32 s1, s3, s1
	s_sub_i32 s3, s1, s0
	s_cmp_ge_u32 s1, s0
	s_cselect_b32 s3, s3, s1
	s_cmp_lg_u32 s3, 0
	s_cselect_b64 s[0:1], -1, 0
	s_cmp_ge_i32 s2, s3
	s_cselect_b64 s[4:5], -1, 0
	s_and_b64 s[4:5], s[0:1], s[4:5]
	s_xor_b64 s[6:7], s[0:1], s[4:5]
	s_and_b64 vcc, exec, s[6:7]
	s_cbranch_vccnz .LBB0_132
	s_sub_i32 s6, s30, s3
	s_sub_i32 s3, s2, s3
	s_lshl_b32 s3, s3, 3
	s_add_i32 s3, s57, s3
	s_and_b64 s[4:5], s[4:5], exec
	s_cselect_b32 s3, s3, s34
	s_lshl_b32 s4, s6, 3
	s_and_b64 s[0:1], s[0:1], exec
	s_cselect_b32 s10, s4, s80
	s_mul_i32 s11, s57, 0x2100
	v_lshrrev_b32_e32 v55, 3, v146
	v_and_b32_e32 v56, 7, v146
	v_mul_u32_u24_e32 v44, 0x84, v55
	v_lshl_add_u32 v44, v56, 4, v44
	v_add_u32_e32 v44, s11, v44
	v_add_u32_e32 v45, 0x420, v44
	v_add_u32_e32 v46, 0x840, v44
	v_add_u32_e32 v47, 0xc60, v44
	v_add_u32_e32 v48, 0x1080, v44
	v_add_u32_e32 v49, 0x14a0, v44
	v_add_u32_e32 v50, 0x18c0, v44
	v_add_u32_e32 v51, 0x1ce0, v44
	v_mul_u32_u24_e32 v52, 0x420, v56
	v_lshl_add_u32 v52, v55, 2, v52
	v_add_u32_e32 v52, s11, v52
	s_add_u32 s4, s52, 0x2d00000
	s_addc_u32 s5, s53, 0
	v_lshrrev_b32_e32 v55, 3, v146
	v_and_b32_e32 v56, 7, v146
	s_mov_b32 s11, 0x2000
	v_mul_lo_u32 v53, v55, s11
	v_lshl_add_u32 v53, v56, 4, v53
	s_mov_b32 s11, 0x2c00
	v_mul_lo_u32 v54, v55, s11
	v_lshl_add_u32 v54, v56, 4, v54
	s_mov_b32 s0, s3
	s_cmp_ge_u32 s0, 0x1600
	s_cbranch_scc1 .Lcv_done_p1dn
	s_lshr_b32 s18, s0, 6
	s_and_b32 s19, s0, 63
	s_lshl_b32 s15, s19, 5
	s_mul_i32 s16, s18, 0x80000
	s_lshl_b32 s15, s15, 2
	s_add_u32 s16, s16, s15
	s_add_u32 s6, s20, s16
	s_addc_u32 s7, s21, 0
	global_load_dwordx4 v[64:67], v53, s[6:7]
	s_add_u32 s6, s6, 0x10000
	s_addc_u32 s7, s7, 0
	global_load_dwordx4 v[68:71], v53, s[6:7]
	s_add_u32 s6, s6, 0x10000
	s_addc_u32 s7, s7, 0
	global_load_dwordx4 v[72:75], v53, s[6:7]
	s_add_u32 s6, s6, 0x10000
	s_addc_u32 s7, s7, 0
	global_load_dwordx4 v[76:79], v53, s[6:7]
	s_add_u32 s6, s6, 0x10000
	s_addc_u32 s7, s7, 0
	global_load_dwordx4 v[80:83], v53, s[6:7]
	s_add_u32 s6, s6, 0x10000
	s_addc_u32 s7, s7, 0
	global_load_dwordx4 v[84:87], v53, s[6:7]
	s_add_u32 s6, s6, 0x10000
	s_addc_u32 s7, s7, 0
	global_load_dwordx4 v[88:91], v53, s[6:7]
	s_add_u32 s6, s6, 0x10000
	s_addc_u32 s7, s7, 0
	global_load_dwordx4 v[92:95], v53, s[6:7]
	s_add_u32 s1, s0, s10
	s_cmp_ge_u32 s1, 0x1600
	s_cbranch_scc1 .Lcv_only1_p1dn
	s_lshr_b32 s18, s1, 6
	s_and_b32 s19, s1, 63
	s_lshl_b32 s15, s19, 5
	s_mul_i32 s16, s18, 0x80000
	s_lshl_b32 s15, s15, 2
	s_add_u32 s16, s16, s15
	s_add_u32 s6, s20, s16
	s_addc_u32 s7, s21, 0
	global_load_dwordx4 v[96:99], v53, s[6:7]
	s_add_u32 s6, s6, 0x10000
	s_addc_u32 s7, s7, 0
	global_load_dwordx4 v[100:103], v53, s[6:7]
	s_add_u32 s6, s6, 0x10000
	s_addc_u32 s7, s7, 0
	global_load_dwordx4 v[104:107], v53, s[6:7]
	s_add_u32 s6, s6, 0x10000
	s_addc_u32 s7, s7, 0
	global_load_dwordx4 v[108:111], v53, s[6:7]
	s_add_u32 s6, s6, 0x10000
	s_addc_u32 s7, s7, 0
	global_load_dwordx4 v[112:115], v53, s[6:7]
	s_add_u32 s6, s6, 0x10000
	s_addc_u32 s7, s7, 0
	global_load_dwordx4 v[116:119], v53, s[6:7]
	s_add_u32 s6, s6, 0x10000
	s_addc_u32 s7, s7, 0
	global_load_dwordx4 v[120:123], v53, s[6:7]
	s_add_u32 s6, s6, 0x10000
	s_addc_u32 s7, s7, 0
	global_load_dwordx4 v[124:127], v53, s[6:7]
	s_waitcnt vmcnt(8)
	s_branch .Lcv_procA_p1dn

.Lcv_procA_p1dn:
	s_lshr_b32 s18, s0, 6
	s_and_b32 s19, s0, 63
	ds_write2_b32 v44, v64, v65 offset1:1
	ds_write2_b32 v44, v66, v67 offset0:2 offset1:3
	ds_write2_b32 v45, v68, v69 offset1:1
	ds_write2_b32 v45, v70, v71 offset0:2 offset1:3
	ds_write2_b32 v46, v72, v73 offset1:1
	ds_write2_b32 v46, v74, v75 offset0:2 offset1:3
	ds_write2_b32 v47, v76, v77 offset1:1
	ds_write2_b32 v47, v78, v79 offset0:2 offset1:3
	ds_write2_b32 v48, v80, v81 offset1:1
	ds_write2_b32 v48, v82, v83 offset0:2 offset1:3
	ds_write2_b32 v49, v84, v85 offset1:1
	ds_write2_b32 v49, v86, v87 offset0:2 offset1:3
	ds_write2_b32 v50, v88, v89 offset1:1
	ds_write2_b32 v50, v90, v91 offset0:2 offset1:3
	ds_write2_b32 v51, v92, v93 offset1:1
	ds_write2_b32 v51, v94, v95 offset0:2 offset1:3
	s_mul_i32 s15, s19, 0x58000
	s_lshl_b32 s16, s18, 7
	s_add_u32 s15, s15, s16
	s_add_u32 s8, s4, s15
	s_addc_u32 s9, s5, 0
	s_waitcnt lgkmcnt(0)
	ds_read2_b32 v[8:9], v52 offset0:0 offset1:33
	ds_read2_b32 v[10:11], v52 offset0:66 offset1:99
	ds_read2_b32 v[12:13], v52 offset0:132 offset1:165
	ds_read2_b32 v[14:15], v52 offset0:198 offset1:231
	ds_read2_b32 v[16:17], v52 offset0:8 offset1:41
	ds_read2_b32 v[18:19], v52 offset0:74 offset1:107
	ds_read2_b32 v[20:21], v52 offset0:140 offset1:173
	ds_read2_b32 v[22:23], v52 offset0:206 offset1:239
	ds_read2_b32 v[24:25], v52 offset0:16 offset1:49
	ds_read2_b32 v[26:27], v52 offset0:82 offset1:115
	ds_read2_b32 v[28:29], v52 offset0:148 offset1:181
	ds_read2_b32 v[30:31], v52 offset0:214 offset1:247
	ds_read2_b32 v[32:33], v52 offset0:24 offset1:57
	ds_read2_b32 v[34:35], v52 offset0:90 offset1:123
	ds_read2_b32 v[36:37], v52 offset0:156 offset1:189
	ds_read2_b32 v[38:39], v52 offset0:222 offset1:255
	s_waitcnt lgkmcnt(12)
	v_cvt_pk_bf16_f32 v128, v8, v9
	v_cvt_pk_bf16_f32 v129, v10, v11
	v_cvt_pk_bf16_f32 v130, v12, v13
	v_cvt_pk_bf16_f32 v131, v14, v15
	global_store_dwordx4 v54, v[128:131], s[8:9]
	s_add_u32 s8, s8, 0x16000
	s_addc_u32 s9, s9, 0
	s_waitcnt lgkmcnt(8)
	v_cvt_pk_bf16_f32 v132, v16, v17
	v_cvt_pk_bf16_f32 v133, v18, v19
	v_cvt_pk_bf16_f32 v134, v20, v21
	v_cvt_pk_bf16_f32 v135, v22, v23
	global_store_dwordx4 v54, v[132:135], s[8:9]
	s_add_u32 s8, s8, 0x16000
	s_addc_u32 s9, s9, 0
	s_waitcnt lgkmcnt(4)
	v_cvt_pk_bf16_f32 v136, v24, v25
	v_cvt_pk_bf16_f32 v137, v26, v27
	v_cvt_pk_bf16_f32 v138, v28, v29
	v_cvt_pk_bf16_f32 v139, v30, v31
	global_store_dwordx4 v54, v[136:139], s[8:9]
	s_add_u32 s8, s8, 0x16000
	s_addc_u32 s9, s9, 0
	s_waitcnt lgkmcnt(0)
	v_cvt_pk_bf16_f32 v140, v32, v33
	v_cvt_pk_bf16_f32 v141, v34, v35
	v_cvt_pk_bf16_f32 v142, v36, v37
	v_cvt_pk_bf16_f32 v143, v38, v39
	global_store_dwordx4 v54, v[140:143], s[8:9]
	s_cmp_ge_u32 s1, 0x1600
	s_cbranch_scc1 .Lcv_done_p1dn
	s_add_u32 s0, s1, s10
	s_cmp_ge_u32 s0, 0x1600
	s_cbranch_scc1 .Lcv_tailB_p1dn
	s_lshr_b32 s18, s0, 6
	s_and_b32 s19, s0, 63
	s_lshl_b32 s15, s19, 5
	s_mul_i32 s16, s18, 0x80000
	s_lshl_b32 s15, s15, 2
	s_add_u32 s16, s16, s15
	s_add_u32 s6, s20, s16
	s_addc_u32 s7, s21, 0
	global_load_dwordx4 v[64:67], v53, s[6:7]
	s_add_u32 s6, s6, 0x10000
	s_addc_u32 s7, s7, 0
	global_load_dwordx4 v[68:71], v53, s[6:7]
	s_add_u32 s6, s6, 0x10000
	s_addc_u32 s7, s7, 0
	global_load_dwordx4 v[72:75], v53, s[6:7]
	s_add_u32 s6, s6, 0x10000
	s_addc_u32 s7, s7, 0
	global_load_dwordx4 v[76:79], v53, s[6:7]
	s_add_u32 s6, s6, 0x10000
	s_addc_u32 s7, s7, 0
	global_load_dwordx4 v[80:83], v53, s[6:7]
	s_add_u32 s6, s6, 0x10000
	s_addc_u32 s7, s7, 0
	global_load_dwordx4 v[84:87], v53, s[6:7]
	s_add_u32 s6, s6, 0x10000
	s_addc_u32 s7, s7, 0
	global_load_dwordx4 v[88:91], v53, s[6:7]
	s_add_u32 s6, s6, 0x10000
	s_addc_u32 s7, s7, 0
	global_load_dwordx4 v[92:95], v53, s[6:7]
	s_waitcnt vmcnt(12)
	s_branch .Lcv_procB_p1dn
.Lcv_tailB_p1dn:
	s_waitcnt vmcnt(4)
.Lcv_procB_p1dn:
	s_lshr_b32 s18, s1, 6
	s_and_b32 s19, s1, 63
	ds_write2_b32 v44, v96, v97 offset1:1
	ds_write2_b32 v44, v98, v99 offset0:2 offset1:3
	ds_write2_b32 v45, v100, v101 offset1:1
	ds_write2_b32 v45, v102, v103 offset0:2 offset1:3
	ds_write2_b32 v46, v104, v105 offset1:1
	ds_write2_b32 v46, v106, v107 offset0:2 offset1:3
	ds_write2_b32 v47, v108, v109 offset1:1
	ds_write2_b32 v47, v110, v111 offset0:2 offset1:3
	ds_write2_b32 v48, v112, v113 offset1:1
	ds_write2_b32 v48, v114, v115 offset0:2 offset1:3
	ds_write2_b32 v49, v116, v117 offset1:1
	ds_write2_b32 v49, v118, v119 offset0:2 offset1:3
	ds_write2_b32 v50, v120, v121 offset1:1
	ds_write2_b32 v50, v122, v123 offset0:2 offset1:3
	ds_write2_b32 v51, v124, v125 offset1:1
	ds_write2_b32 v51, v126, v127 offset0:2 offset1:3
	s_mul_i32 s15, s19, 0x58000
	s_lshl_b32 s16, s18, 7
	s_add_u32 s15, s15, s16
	s_add_u32 s8, s4, s15
	s_addc_u32 s9, s5, 0
	s_waitcnt lgkmcnt(0)
	ds_read2_b32 v[8:9], v52 offset0:0 offset1:33
	ds_read2_b32 v[10:11], v52 offset0:66 offset1:99
	ds_read2_b32 v[12:13], v52 offset0:132 offset1:165
	ds_read2_b32 v[14:15], v52 offset0:198 offset1:231
	ds_read2_b32 v[16:17], v52 offset0:8 offset1:41
	ds_read2_b32 v[18:19], v52 offset0:74 offset1:107
	ds_read2_b32 v[20:21], v52 offset0:140 offset1:173
	ds_read2_b32 v[22:23], v52 offset0:206 offset1:239
	ds_read2_b32 v[24:25], v52 offset0:16 offset1:49
	ds_read2_b32 v[26:27], v52 offset0:82 offset1:115
	ds_read2_b32 v[28:29], v52 offset0:148 offset1:181
	ds_read2_b32 v[30:31], v52 offset0:214 offset1:247
	ds_read2_b32 v[32:33], v52 offset0:24 offset1:57
	ds_read2_b32 v[34:35], v52 offset0:90 offset1:123
	ds_read2_b32 v[36:37], v52 offset0:156 offset1:189
	ds_read2_b32 v[38:39], v52 offset0:222 offset1:255
	s_waitcnt lgkmcnt(12)
	v_cvt_pk_bf16_f32 v128, v8, v9
	v_cvt_pk_bf16_f32 v129, v10, v11
	v_cvt_pk_bf16_f32 v130, v12, v13
	v_cvt_pk_bf16_f32 v131, v14, v15
	global_store_dwordx4 v54, v[128:131], s[8:9]
	s_add_u32 s8, s8, 0x16000
	s_addc_u32 s9, s9, 0
	s_waitcnt lgkmcnt(8)
	v_cvt_pk_bf16_f32 v132, v16, v17
	v_cvt_pk_bf16_f32 v133, v18, v19
	v_cvt_pk_bf16_f32 v134, v20, v21
	v_cvt_pk_bf16_f32 v135, v22, v23
	global_store_dwordx4 v54, v[132:135], s[8:9]
	s_add_u32 s8, s8, 0x16000
	s_addc_u32 s9, s9, 0
	s_waitcnt lgkmcnt(4)
	v_cvt_pk_bf16_f32 v136, v24, v25
	v_cvt_pk_bf16_f32 v137, v26, v27
	v_cvt_pk_bf16_f32 v138, v28, v29
	v_cvt_pk_bf16_f32 v139, v30, v31
	global_store_dwordx4 v54, v[136:139], s[8:9]
	s_add_u32 s8, s8, 0x16000
	s_addc_u32 s9, s9, 0
	s_waitcnt lgkmcnt(0)
	v_cvt_pk_bf16_f32 v140, v32, v33
	v_cvt_pk_bf16_f32 v141, v34, v35
	v_cvt_pk_bf16_f32 v142, v36, v37
	v_cvt_pk_bf16_f32 v143, v38, v39
	global_store_dwordx4 v54, v[140:143], s[8:9]
	s_cmp_ge_u32 s0, 0x1600
	s_cbranch_scc1 .Lcv_done_p1dn
	s_add_u32 s1, s0, s10
	s_cmp_ge_u32 s1, 0x1600
	s_cbranch_scc1 .Lcv_tailA_p1dn
	s_lshr_b32 s18, s1, 6
	s_and_b32 s19, s1, 63
	s_lshl_b32 s15, s19, 5
	s_mul_i32 s16, s18, 0x80000
	s_lshl_b32 s15, s15, 2
	s_add_u32 s16, s16, s15
	s_add_u32 s6, s20, s16
	s_addc_u32 s7, s21, 0
	global_load_dwordx4 v[96:99], v53, s[6:7]
	s_add_u32 s6, s6, 0x10000
	s_addc_u32 s7, s7, 0
	global_load_dwordx4 v[100:103], v53, s[6:7]
	s_add_u32 s6, s6, 0x10000
	s_addc_u32 s7, s7, 0
	global_load_dwordx4 v[104:107], v53, s[6:7]
	s_add_u32 s6, s6, 0x10000
	s_addc_u32 s7, s7, 0
	global_load_dwordx4 v[108:111], v53, s[6:7]
	s_add_u32 s6, s6, 0x10000
	s_addc_u32 s7, s7, 0
	global_load_dwordx4 v[112:115], v53, s[6:7]
	s_add_u32 s6, s6, 0x10000
	s_addc_u32 s7, s7, 0
	global_load_dwordx4 v[116:119], v53, s[6:7]
	s_add_u32 s6, s6, 0x10000
	s_addc_u32 s7, s7, 0
	global_load_dwordx4 v[120:123], v53, s[6:7]
	s_add_u32 s6, s6, 0x10000
	s_addc_u32 s7, s7, 0
	global_load_dwordx4 v[124:127], v53, s[6:7]
	s_waitcnt vmcnt(12)
	s_branch .Lcv_procA_p1dn
.Lcv_tailA_p1dn:
	s_waitcnt vmcnt(4)
	s_branch .Lcv_procA_p1dn
.Lcv_done_p1dn:
	s_add_u32 s4, s52, 0x4300000
	s_addc_u32 s5, s53, 0
	v_lshrrev_b32_e32 v55, 3, v146
	v_and_b32_e32 v56, 7, v146
	s_mov_b32 s11, 0xa740
	v_mul_lo_u32 v53, v55, s11
	v_lshl_add_u32 v53, v56, 4, v53
	s_mov_b32 s11, 0x1000
	v_mul_lo_u32 v54, v55, s11
	v_lshl_add_u32 v54, v56, 4, v54
	s_mov_b32 s0, s3
	s_cmp_ge_u32 s0, 0x2a00
	s_cbranch_scc1 .Lcv_done_p1win
	s_mul_hi_u32 s18, s0, 0xc30c31
	s_mul_i32 s19, s18, 336
	s_sub_u32 s19, s0, s19
	s_mov_b32 s16, 0
	s_cmp_ge_u32 s19, 96
	s_cselect_b32 s16, 16, s16
	s_cmp_ge_u32 s19, 192
	s_cselect_b32 s16, 464, s16
	s_cmp_ge_u32 s19, 320
	s_cselect_b32 s16, -7168, s16
	s_cmp_ge_u32 s19, 321
	s_cselect_b32 s16, -4112, s16
	s_cmp_ge_u32 s19, 328
	s_cselect_b32 s16, -4144, s16
	s_lshl_b32 s15, s19, 5
	s_add_i32 s15, s15, s16
	s_mul_i32 s16, s18, 0x29d000
	s_lshl_b32 s15, s15, 2
	s_add_u32 s16, s16, s15
	s_add_u32 s6, s24, s16
	s_addc_u32 s7, s25, 0
	global_load_dwordx4 v[64:67], v53, s[6:7]
	s_add_u32 s6, s6, 0x53a00
	s_addc_u32 s7, s7, 0
	global_load_dwordx4 v[68:71], v53, s[6:7]
	s_add_u32 s6, s6, 0x53a00
	s_addc_u32 s7, s7, 0
	global_load_dwordx4 v[72:75], v53, s[6:7]
	s_add_u32 s6, s6, 0x53a00
	s_addc_u32 s7, s7, 0
	global_load_dwordx4 v[76:79], v53, s[6:7]
	s_add_u32 s6, s6, 0x53a00
	s_addc_u32 s7, s7, 0
	global_load_dwordx4 v[80:83], v53, s[6:7]
	s_add_u32 s6, s6, 0x53a00
	s_addc_u32 s7, s7, 0
	global_load_dwordx4 v[84:87], v53, s[6:7]
	s_add_u32 s6, s6, 0x53a00
	s_addc_u32 s7, s7, 0
	global_load_dwordx4 v[88:91], v53, s[6:7]
	s_add_u32 s6, s6, 0x53a00
	s_addc_u32 s7, s7, 0
	global_load_dwordx4 v[92:95], v53, s[6:7]
	s_add_u32 s1, s0, s10
	s_cmp_ge_u32 s1, 0x2a00
	s_cbranch_scc1 .Lcv_only1_p1win
	s_mul_hi_u32 s18, s1, 0xc30c31
	s_mul_i32 s19, s18, 336
	s_sub_u32 s19, s1, s19
	s_mov_b32 s16, 0
	s_cmp_ge_u32 s19, 96
	s_cselect_b32 s16, 16, s16
	s_cmp_ge_u32 s19, 192
	s_cselect_b32 s16, 464, s16
	s_cmp_ge_u32 s19, 320
	s_cselect_b32 s16, -7168, s16
	s_cmp_ge_u32 s19, 321
	s_cselect_b32 s16, -4112, s16
	s_cmp_ge_u32 s19, 328
	s_cselect_b32 s16, -4144, s16
	s_lshl_b32 s15, s19, 5
	s_add_i32 s15, s15, s16
	s_mul_i32 s16, s18, 0x29d000
	s_lshl_b32 s15, s15, 2
	s_add_u32 s16, s16, s15
	s_add_u32 s6, s24, s16
	s_addc_u32 s7, s25, 0
	global_load_dwordx4 v[96:99], v53, s[6:7]
	s_add_u32 s6, s6, 0x53a00
	s_addc_u32 s7, s7, 0
	global_load_dwordx4 v[100:103], v53, s[6:7]
	s_add_u32 s6, s6, 0x53a00
	s_addc_u32 s7, s7, 0
	global_load_dwordx4 v[104:107], v53, s[6:7]
	s_add_u32 s6, s6, 0x53a00
	s_addc_u32 s7, s7, 0
	global_load_dwordx4 v[108:111], v53, s[6:7]
	s_add_u32 s6, s6, 0x53a00
	s_addc_u32 s7, s7, 0
	global_load_dwordx4 v[112:115], v53, s[6:7]
	s_add_u32 s6, s6, 0x53a00
	s_addc_u32 s7, s7, 0
	global_load_dwordx4 v[116:119], v53, s[6:7]
	s_add_u32 s6, s6, 0x53a00
	s_addc_u32 s7, s7, 0
	global_load_dwordx4 v[120:123], v53, s[6:7]
	s_add_u32 s6, s6, 0x53a00
	s_addc_u32 s7, s7, 0
	global_load_dwordx4 v[124:127], v53, s[6:7]
	s_waitcnt vmcnt(8)
	s_branch .Lcv_procA_p1win

.Lcv_procA_p1win:
	s_mul_hi_u32 s18, s0, 0xc30c31
	s_mul_i32 s19, s18, 336
	s_sub_u32 s19, s0, s19
	s_cmp_eq_u32 s19, 320
	s_cselect_b32 s15, 0xf0f0f0f0, 0
	s_cmp_eq_u32 s19, 327
	s_cselect_b32 s15, -1, s15
	s_cmp_eq_u32 s15, 0
	s_cbranch_scc1 .Lcv_nz_p1win_A
	s_mov_b32 exec_lo, s15
	s_mov_b32 exec_hi, s15
	v_mov_b32_e32 v64, 0
	v_mov_b32_e32 v65, 0
	v_mov_b32_e32 v66, 0
	v_mov_b32_e32 v67, 0
	v_mov_b32_e32 v68, 0
	v_mov_b32_e32 v69, 0
	v_mov_b32_e32 v70, 0
	v_mov_b32_e32 v71, 0
	v_mov_b32_e32 v72, 0
	v_mov_b32_e32 v73, 0
	v_mov_b32_e32 v74, 0
	v_mov_b32_e32 v75, 0
	v_mov_b32_e32 v76, 0
	v_mov_b32_e32 v77, 0
	v_mov_b32_e32 v78, 0
	v_mov_b32_e32 v79, 0
	v_mov_b32_e32 v80, 0
	v_mov_b32_e32 v81, 0
	v_mov_b32_e32 v82, 0
	v_mov_b32_e32 v83, 0
	v_mov_b32_e32 v84, 0
	v_mov_b32_e32 v85, 0
	v_mov_b32_e32 v86, 0
	v_mov_b32_e32 v87, 0
	v_mov_b32_e32 v88, 0
	v_mov_b32_e32 v89, 0
	v_mov_b32_e32 v90, 0
	v_mov_b32_e32 v91, 0
	v_mov_b32_e32 v92, 0
	v_mov_b32_e32 v93, 0
	v_mov_b32_e32 v94, 0
	v_mov_b32_e32 v95, 0
	s_mov_b64 exec, -1
.Lcv_nz_p1win_A:
	ds_write2_b32 v44, v64, v65 offset1:1
	ds_write2_b32 v44, v66, v67 offset0:2 offset1:3
	ds_write2_b32 v45, v68, v69 offset1:1
	ds_write2_b32 v45, v70, v71 offset0:2 offset1:3
	ds_write2_b32 v46, v72, v73 offset1:1
	ds_write2_b32 v46, v74, v75 offset0:2 offset1:3
	ds_write2_b32 v47, v76, v77 offset1:1
	ds_write2_b32 v47, v78, v79 offset0:2 offset1:3
	ds_write2_b32 v48, v80, v81 offset1:1
	ds_write2_b32 v48, v82, v83 offset0:2 offset1:3
	ds_write2_b32 v49, v84, v85 offset1:1
	ds_write2_b32 v49, v86, v87 offset0:2 offset1:3
	ds_write2_b32 v50, v88, v89 offset1:1
	ds_write2_b32 v50, v90, v91 offset0:2 offset1:3
	ds_write2_b32 v51, v92, v93 offset1:1
	ds_write2_b32 v51, v94, v95 offset0:2 offset1:3
	s_mul_i32 s15, s19, 0x20000
	s_lshl_b32 s16, s18, 7
	s_add_u32 s15, s15, s16
	s_add_u32 s8, s4, s15
	s_addc_u32 s9, s5, 0
	s_waitcnt lgkmcnt(0)
	ds_read2_b32 v[8:9], v52 offset0:0 offset1:33
	ds_read2_b32 v[10:11], v52 offset0:66 offset1:99
	ds_read2_b32 v[12:13], v52 offset0:132 offset1:165
	ds_read2_b32 v[14:15], v52 offset0:198 offset1:231
	ds_read2_b32 v[16:17], v52 offset0:8 offset1:41
	ds_read2_b32 v[18:19], v52 offset0:74 offset1:107
	ds_read2_b32 v[20:21], v52 offset0:140 offset1:173
	ds_read2_b32 v[22:23], v52 offset0:206 offset1:239
	ds_read2_b32 v[24:25], v52 offset0:16 offset1:49
	ds_read2_b32 v[26:27], v52 offset0:82 offset1:115
	ds_read2_b32 v[28:29], v52 offset0:148 offset1:181
	ds_read2_b32 v[30:31], v52 offset0:214 offset1:247
	ds_read2_b32 v[32:33], v52 offset0:24 offset1:57
	ds_read2_b32 v[34:35], v52 offset0:90 offset1:123
	ds_read2_b32 v[36:37], v52 offset0:156 offset1:189
	ds_read2_b32 v[38:39], v52 offset0:222 offset1:255
	s_waitcnt lgkmcnt(12)
	v_cvt_pk_bf16_f32 v128, v8, v9
	v_cvt_pk_bf16_f32 v129, v10, v11
	v_cvt_pk_bf16_f32 v130, v12, v13
	v_cvt_pk_bf16_f32 v131, v14, v15
	global_store_dwordx4 v54, v[128:131], s[8:9]
	s_add_u32 s8, s8, 0x8000
	s_addc_u32 s9, s9, 0
	s_waitcnt lgkmcnt(8)
	v_cvt_pk_bf16_f32 v132, v16, v17
	v_cvt_pk_bf16_f32 v133, v18, v19
	v_cvt_pk_bf16_f32 v134, v20, v21
	v_cvt_pk_bf16_f32 v135, v22, v23
	global_store_dwordx4 v54, v[132:135], s[8:9]
	s_add_u32 s8, s8, 0x8000
	s_addc_u32 s9, s9, 0
	s_waitcnt lgkmcnt(4)
	v_cvt_pk_bf16_f32 v136, v24, v25
	v_cvt_pk_bf16_f32 v137, v26, v27
	v_cvt_pk_bf16_f32 v138, v28, v29
	v_cvt_pk_bf16_f32 v139, v30, v31
	global_store_dwordx4 v54, v[136:139], s[8:9]
	s_add_u32 s8, s8, 0x8000
	s_addc_u32 s9, s9, 0
	s_waitcnt lgkmcnt(0)
	v_cvt_pk_bf16_f32 v140, v32, v33
	v_cvt_pk_bf16_f32 v141, v34, v35
	v_cvt_pk_bf16_f32 v142, v36, v37
	v_cvt_pk_bf16_f32 v143, v38, v39
	global_store_dwordx4 v54, v[140:143], s[8:9]
	s_cmp_ge_u32 s1, 0x2a00
	s_cbranch_scc1 .Lcv_done_p1win
	s_add_u32 s0, s1, s10
	s_cmp_ge_u32 s0, 0x2a00
	s_cbranch_scc1 .Lcv_tailB_p1win
	s_mul_hi_u32 s18, s0, 0xc30c31
	s_mul_i32 s19, s18, 336
	s_sub_u32 s19, s0, s19
	s_mov_b32 s16, 0
	s_cmp_ge_u32 s19, 96
	s_cselect_b32 s16, 16, s16
	s_cmp_ge_u32 s19, 192
	s_cselect_b32 s16, 464, s16
	s_cmp_ge_u32 s19, 320
	s_cselect_b32 s16, -7168, s16
	s_cmp_ge_u32 s19, 321
	s_cselect_b32 s16, -4112, s16
	s_cmp_ge_u32 s19, 328
	s_cselect_b32 s16, -4144, s16
	s_lshl_b32 s15, s19, 5
	s_add_i32 s15, s15, s16
	s_mul_i32 s16, s18, 0x29d000
	s_lshl_b32 s15, s15, 2
	s_add_u32 s16, s16, s15
	s_add_u32 s6, s24, s16
	s_addc_u32 s7, s25, 0
	global_load_dwordx4 v[64:67], v53, s[6:7]
	s_add_u32 s6, s6, 0x53a00
	s_addc_u32 s7, s7, 0
	global_load_dwordx4 v[68:71], v53, s[6:7]
	s_add_u32 s6, s6, 0x53a00
	s_addc_u32 s7, s7, 0
	global_load_dwordx4 v[72:75], v53, s[6:7]
	s_add_u32 s6, s6, 0x53a00
	s_addc_u32 s7, s7, 0
	global_load_dwordx4 v[76:79], v53, s[6:7]
	s_add_u32 s6, s6, 0x53a00
	s_addc_u32 s7, s7, 0
	global_load_dwordx4 v[80:83], v53, s[6:7]
	s_add_u32 s6, s6, 0x53a00
	s_addc_u32 s7, s7, 0
	global_load_dwordx4 v[84:87], v53, s[6:7]
	s_add_u32 s6, s6, 0x53a00
	s_addc_u32 s7, s7, 0
	global_load_dwordx4 v[88:91], v53, s[6:7]
	s_add_u32 s6, s6, 0x53a00
	s_addc_u32 s7, s7, 0
	global_load_dwordx4 v[92:95], v53, s[6:7]
	s_waitcnt vmcnt(12)
	s_branch .Lcv_procB_p1win

.Lcv_procB_p1win:
	s_mul_hi_u32 s18, s1, 0xc30c31
	s_mul_i32 s19, s18, 336
	s_sub_u32 s19, s1, s19
	s_cmp_eq_u32 s19, 320
	s_cselect_b32 s15, 0xf0f0f0f0, 0
	s_cmp_eq_u32 s19, 327
	s_cselect_b32 s15, -1, s15
	s_cmp_eq_u32 s15, 0
	s_cbranch_scc1 .Lcv_nz_p1win_B
	s_mov_b32 exec_lo, s15
	s_mov_b32 exec_hi, s15
	v_mov_b32_e32 v96, 0
	v_mov_b32_e32 v97, 0
	v_mov_b32_e32 v98, 0
	v_mov_b32_e32 v99, 0
	v_mov_b32_e32 v100, 0
	v_mov_b32_e32 v101, 0
	v_mov_b32_e32 v102, 0
	v_mov_b32_e32 v103, 0
	v_mov_b32_e32 v104, 0
	v_mov_b32_e32 v105, 0
	v_mov_b32_e32 v106, 0
	v_mov_b32_e32 v107, 0
	v_mov_b32_e32 v108, 0
	v_mov_b32_e32 v109, 0
	v_mov_b32_e32 v110, 0
	v_mov_b32_e32 v111, 0
	v_mov_b32_e32 v112, 0
	v_mov_b32_e32 v113, 0
	v_mov_b32_e32 v114, 0
	v_mov_b32_e32 v115, 0
	v_mov_b32_e32 v116, 0
	v_mov_b32_e32 v117, 0
	v_mov_b32_e32 v118, 0
	v_mov_b32_e32 v119, 0
	v_mov_b32_e32 v120, 0
	v_mov_b32_e32 v121, 0
	v_mov_b32_e32 v122, 0
	v_mov_b32_e32 v123, 0
	v_mov_b32_e32 v124, 0
	v_mov_b32_e32 v125, 0
	v_mov_b32_e32 v126, 0
	v_mov_b32_e32 v127, 0
	s_mov_b64 exec, -1
.Lcv_nz_p1win_B:
	ds_write2_b32 v44, v96, v97 offset1:1
	ds_write2_b32 v44, v98, v99 offset0:2 offset1:3
	ds_write2_b32 v45, v100, v101 offset1:1
	ds_write2_b32 v45, v102, v103 offset0:2 offset1:3
	ds_write2_b32 v46, v104, v105 offset1:1
	ds_write2_b32 v46, v106, v107 offset0:2 offset1:3
	ds_write2_b32 v47, v108, v109 offset1:1
	ds_write2_b32 v47, v110, v111 offset0:2 offset1:3
	ds_write2_b32 v48, v112, v113 offset1:1
	ds_write2_b32 v48, v114, v115 offset0:2 offset1:3
	ds_write2_b32 v49, v116, v117 offset1:1
	ds_write2_b32 v49, v118, v119 offset0:2 offset1:3
	ds_write2_b32 v50, v120, v121 offset1:1
	ds_write2_b32 v50, v122, v123 offset0:2 offset1:3
	ds_write2_b32 v51, v124, v125 offset1:1
	ds_write2_b32 v51, v126, v127 offset0:2 offset1:3
	s_mul_i32 s15, s19, 0x20000
	s_lshl_b32 s16, s18, 7
	s_add_u32 s15, s15, s16
	s_add_u32 s8, s4, s15
	s_addc_u32 s9, s5, 0
	s_waitcnt lgkmcnt(0)
	ds_read2_b32 v[8:9], v52 offset0:0 offset1:33
	ds_read2_b32 v[10:11], v52 offset0:66 offset1:99
	ds_read2_b32 v[12:13], v52 offset0:132 offset1:165
	ds_read2_b32 v[14:15], v52 offset0:198 offset1:231
	ds_read2_b32 v[16:17], v52 offset0:8 offset1:41
	ds_read2_b32 v[18:19], v52 offset0:74 offset1:107
	ds_read2_b32 v[20:21], v52 offset0:140 offset1:173
	ds_read2_b32 v[22:23], v52 offset0:206 offset1:239
	ds_read2_b32 v[24:25], v52 offset0:16 offset1:49
	ds_read2_b32 v[26:27], v52 offset0:82 offset1:115
	ds_read2_b32 v[28:29], v52 offset0:148 offset1:181
	ds_read2_b32 v[30:31], v52 offset0:214 offset1:247
	ds_read2_b32 v[32:33], v52 offset0:24 offset1:57
	ds_read2_b32 v[34:35], v52 offset0:90 offset1:123
	ds_read2_b32 v[36:37], v52 offset0:156 offset1:189
	ds_read2_b32 v[38:39], v52 offset0:222 offset1:255
	s_waitcnt lgkmcnt(12)
	v_cvt_pk_bf16_f32 v128, v8, v9
	v_cvt_pk_bf16_f32 v129, v10, v11
	v_cvt_pk_bf16_f32 v130, v12, v13
	v_cvt_pk_bf16_f32 v131, v14, v15
	global_store_dwordx4 v54, v[128:131], s[8:9]
	s_add_u32 s8, s8, 0x8000
	s_addc_u32 s9, s9, 0
	s_waitcnt lgkmcnt(8)
	v_cvt_pk_bf16_f32 v132, v16, v17
	v_cvt_pk_bf16_f32 v133, v18, v19
	v_cvt_pk_bf16_f32 v134, v20, v21
	v_cvt_pk_bf16_f32 v135, v22, v23
	global_store_dwordx4 v54, v[132:135], s[8:9]
	s_add_u32 s8, s8, 0x8000
	s_addc_u32 s9, s9, 0
	s_waitcnt lgkmcnt(4)
	v_cvt_pk_bf16_f32 v136, v24, v25
	v_cvt_pk_bf16_f32 v137, v26, v27
	v_cvt_pk_bf16_f32 v138, v28, v29
	v_cvt_pk_bf16_f32 v139, v30, v31
	global_store_dwordx4 v54, v[136:139], s[8:9]
	s_add_u32 s8, s8, 0x8000
	s_addc_u32 s9, s9, 0
	s_waitcnt lgkmcnt(0)
	v_cvt_pk_bf16_f32 v140, v32, v33
	v_cvt_pk_bf16_f32 v141, v34, v35
	v_cvt_pk_bf16_f32 v142, v36, v37
	v_cvt_pk_bf16_f32 v143, v38, v39
	global_store_dwordx4 v54, v[140:143], s[8:9]
	s_cmp_ge_u32 s0, 0x2a00
	s_cbranch_scc1 .Lcv_done_p1win
	s_add_u32 s1, s0, s10
	s_cmp_ge_u32 s1, 0x2a00
	s_cbranch_scc1 .Lcv_tailA_p1win
	s_mul_hi_u32 s18, s1, 0xc30c31
	s_mul_i32 s19, s18, 336
	s_sub_u32 s19, s1, s19
	s_mov_b32 s16, 0
	s_cmp_ge_u32 s19, 96
	s_cselect_b32 s16, 16, s16
	s_cmp_ge_u32 s19, 192
	s_cselect_b32 s16, 464, s16
	s_cmp_ge_u32 s19, 320
	s_cselect_b32 s16, -7168, s16
	s_cmp_ge_u32 s19, 321
	s_cselect_b32 s16, -4112, s16
	s_cmp_ge_u32 s19, 328
	s_cselect_b32 s16, -4144, s16
	s_lshl_b32 s15, s19, 5
	s_add_i32 s15, s15, s16
	s_mul_i32 s16, s18, 0x29d000
	s_lshl_b32 s15, s15, 2
	s_add_u32 s16, s16, s15
	s_add_u32 s6, s24, s16
	s_addc_u32 s7, s25, 0
	global_load_dwordx4 v[96:99], v53, s[6:7]
	s_add_u32 s6, s6, 0x53a00
	s_addc_u32 s7, s7, 0
	global_load_dwordx4 v[100:103], v53, s[6:7]
	s_add_u32 s6, s6, 0x53a00
	s_addc_u32 s7, s7, 0
	global_load_dwordx4 v[104:107], v53, s[6:7]
	s_add_u32 s6, s6, 0x53a00
	s_addc_u32 s7, s7, 0
	global_load_dwordx4 v[108:111], v53, s[6:7]
	s_add_u32 s6, s6, 0x53a00
	s_addc_u32 s7, s7, 0
	global_load_dwordx4 v[112:115], v53, s[6:7]
	s_add_u32 s6, s6, 0x53a00
	s_addc_u32 s7, s7, 0
	global_load_dwordx4 v[116:119], v53, s[6:7]
	s_add_u32 s6, s6, 0x53a00
	s_addc_u32 s7, s7, 0
	global_load_dwordx4 v[120:123], v53, s[6:7]
	s_add_u32 s6, s6, 0x53a00
	s_addc_u32 s7, s7, 0
	global_load_dwordx4 v[124:127], v53, s[6:7]
	s_waitcnt vmcnt(12)
	s_branch .Lcv_procA_p1win

.Lcv_done_p1win:
.LBB0_132:
	s_waitcnt vmcnt(0)
	s_waitcnt vmcnt(0)
	s_barrier
	s_mov_b64 s[0:1], exec
	v_readlane_b32 s4, v240, 9
	v_readlane_b32 s5, v240, 10
	s_and_b64 s[4:5], s[0:1], s[4:5]
	s_mov_b64 exec, s[4:5]
	s_cbranch_execz .LBB0_184
	s_add_i32 s3, 0, 0x23fc0
	v_mov_b32_e32 v0, s3
	s_waitcnt vmcnt(0) expcnt(0) lgkmcnt(0)
	ds_read_b32 v2, v0
	s_add_i32 s3, 0, 0x23fc4
	v_mov_b32_e32 v0, s3
	ds_read_b32 v0, v0
	s_waitcnt lgkmcnt(1)
	v_cmp_ne_u32_e32 vcc, 0, v2
	s_cbranch_vccnz .LBB0_148
	s_add_u32 s4, s52, 0x40200
	s_addc_u32 s5, s53, 0
	s_add_u32 s6, s52, 0x40400
	s_addc_u32 s7, s53, 0
	s_add_u32 s8, s52, 0x40500
	s_addc_u32 s9, s53, 0
	s_add_u32 s14, s52, 0x40600
	s_addc_u32 s15, s53, 0
	s_add_u32 s16, s52, 0x40700
	s_addc_u32 s17, s53, 0
	s_add_u32 s18, s52, 0x40800
	s_addc_u32 s19, s53, 0
	s_add_u32 s20, s52, 0x40900
	s_addc_u32 s21, s53, 0
	s_add_u32 s24, s52, 0x40a00
	s_addc_u32 s25, s53, 0
	s_add_u32 s84, s52, 0x40b00
	s_addc_u32 s85, s53, 0
	s_add_u32 s86, s52, 0x40c00
	s_addc_u32 s87, s53, 0
	s_add_u32 s88, s52, 0x40d00
	s_addc_u32 s89, s53, 0
	s_add_u32 s90, s52, 0x40e00
	s_addc_u32 s91, s53, 0
	s_add_u32 s92, s52, 0x40f00
	s_addc_u32 s93, s53, 0
	s_add_u32 s94, s52, 0x41000
	s_addc_u32 s95, s53, 0
	s_add_u32 s96, s52, 0x41100
	s_addc_u32 s97, s53, 0
	s_add_u32 s10, s52, 0x41200
	v_readlane_b32 s3, v240, 0
	s_addc_u32 s11, s53, 0
	s_mul_i32 s3, s31, s3
	s_add_u32 s28, s52, 0x41300
	s_mul_i32 s3, s3, s30
	s_addc_u32 s29, s53, 0
	s_mov_b32 s35, 1
	v_mov_b32_e32 v16, 0
	s_branch .LBB0_136
